# combo9 + attention tile prologue: Q loads issued with the mask-row loads (one memory round trip per tile prologue instead of two)
# baseline (speedup 1.0000x reference)
.LBB0_1620:
	s_and_b64 s[0:1], s[48:49], exec
	s_mov_b32 m0, s63
	s_cselect_b32 s78, s76, s67
	s_add_i32 s79, s63, 0x8000
	s_waitcnt lgkmcnt(0)
	s_barrier
	global_load_lds_dwordx4 v[148:149], off
	s_mov_b32 m0, s79
	s_add_i32 s80, s63, 0x400
	s_lshl_b32 s77, s78, 6
	global_load_lds_dwordx4 v[150:151], off
	s_mov_b32 m0, s80
	s_add_i32 s81, s63, 0x8400
	global_load_lds_dwordx4 v[152:153], off
	s_mov_b32 m0, s81
	s_or_b32 s0, s20, s77
	s_mov_b32 s1, s21
	v_mov_b32_e32 v9, v252
	global_load_lds_dwordx4 v[154:155], off
	s_lshl_b64 s[0:1], s[0:1], 8
	s_add_u32 s0, s52, s0
	v_add_u32_e32 v10, 0x200, v9
	v_lshlrev_b32_e32 v0, 2, v9
	v_lshlrev_b32_e32 v2, 2, v10
	s_addc_u32 s1, s53, s1
	v_ashrrev_i32_e32 v1, 31, v0
	v_ashrrev_i32_e32 v3, 31, v2
	v_lshl_add_u64 v[0:1], v[0:1], 2, s[0:1]
	v_lshl_add_u64 v[4:5], v[2:3], 2, s[0:1]
	global_load_dwordx4 v[236:239], v[0:1], off
	s_nop 0
	global_load_dwordx4 v[240:243], v[4:5], off
	v_lshlrev_b32_e32 v11, 4, v9
	v_and_b32_e32 v11, 0xf0, v11
	v_add_u32_e32 v138, s77, v169
	v_ashrrev_i32_e32 v9, 4, v9
	v_ashrrev_i32_e32 v14, 4, v10
	v_add_u32_e32 v10, s51, v11
	v_mov_b32_e32 v32, v166
	v_mov_b32_e32 v8, v138
	v_mad_u64_u32 v[244:245], s[0:1], v9, s50, v[10:11]
	v_mad_u64_u32 v[246:247], s[0:1], v14, s50, v[10:11]
	s_mov_b32 s82, 0
	s_cmp_eq_u32 s78, 0
	v_ashrrev_i32_e32 v9, 31, v8
	v_lshl_add_u64 v[2:3], s[20:21], 0, v[8:9]
	v_lshlrev_b32_e32 v0, 3, v32
	v_lshlrev_b64 v[2:3], 12, v[2:3]
	v_ashrrev_i32_e32 v1, 31, v0
	v_lshl_add_u64 v[2:3], s[22:23], 0, v[2:3]
	v_lshl_add_u64 v[16:17], v[0:1], 1, v[2:3]
	global_load_dwordx4 v[28:31], v[16:17], off
	global_load_dwordx4 v[12:15], v[16:17], off offset:224
	global_load_dwordx4 v[24:27], v[16:17], off offset:128
	global_load_dwordx4 v[8:11], v[16:17], off offset:96
	global_load_dwordx4 v[4:7], v[16:17], off offset:64
	global_load_dwordx4 v[0:3], v[16:17], off offset:32
	global_load_dwordx4 v[20:23], v[16:17], off offset:160
	s_nop 0
	global_load_dwordx4 v[16:19], v[16:17], off offset:192
	s_waitcnt vmcnt(8)
	ds_write2_b64 v244, v[236:237], v[238:239] offset1:1
	ds_write2_b64 v246, v[240:241], v[242:243] offset1:1
	s_nop 0
	v_lshl_add_u32 v32, v32, 5, 0
	v_add_u32_e32 v129, 0x15800, v32
	ds_read_b128 v[32:35], v129
	ds_read_b128 v[36:39], v129 offset:16
	ds_read_b128 v[56:59], v129 offset:64
	ds_read_b128 v[60:63], v129 offset:80
	ds_read_b128 v[64:67], v129 offset:128
	ds_read_b128 v[68:71], v129 offset:144
	ds_read_b128 v[72:75], v129 offset:192
	ds_read_b128 v[48:51], v129 offset:208
	ds_read_b128 v[44:47], v129 offset:256
	ds_read_b128 v[40:43], v129 offset:272
	s_waitcnt vmcnt(0)
	v_cvt_f32_f16_e32 v90, v28
	v_cvt_f32_f16_sdwa v91, v28 dst_sel:DWORD dst_unused:UNUSED_PAD src0_sel:WORD_1
	v_cvt_f32_f16_e32 v28, v29
	v_cvt_f32_f16_sdwa v29, v29 dst_sel:DWORD dst_unused:UNUSED_PAD src0_sel:WORD_1
	v_cvt_f32_f16_e32 v92, v30
	v_cvt_f32_f16_sdwa v93, v30 dst_sel:DWORD dst_unused:UNUSED_PAD src0_sel:WORD_1
	v_pk_mul_f32 v[120:121], v[90:91], v[90:91]
	v_cvt_f32_f16_e32 v88, v2
	v_cvt_f32_f16_sdwa v89, v2 dst_sel:DWORD dst_unused:UNUSED_PAD src0_sel:WORD_1
	v_pk_mul_f32 v[122:123], v[28:29], v[28:29]
	v_add_f32_e32 v2, v120, v121
	v_add_f32_e32 v2, v2, v122
	v_cvt_f32_f16_e32 v86, v0
	v_cvt_f32_f16_sdwa v87, v0 dst_sel:DWORD dst_unused:UNUSED_PAD src0_sel:WORD_1
	v_pk_mul_f32 v[124:125], v[92:93], v[92:93]
	v_add_f32_e32 v2, v2, v123
	v_add_f32_e32 v2, v2, v124
	v_cvt_f32_f16_e32 v0, v1
	v_cvt_f32_f16_sdwa v1, v1 dst_sel:DWORD dst_unused:UNUSED_PAD src0_sel:WORD_1
	v_add_f32_e32 v2, v2, v125
	v_fma_mix_f32 v2, v31, v31, v2 op_sel_hi:[1,1,0]
	v_pk_mul_f32 v[114:115], v[86:87], v[86:87]
	v_fma_mix_f32 v2, v31, v31, v2 op_sel:[1,1,0] op_sel_hi:[1,1,0]
	v_pk_mul_f32 v[116:117], v[0:1], v[0:1]
	v_add_f32_e32 v2, v2, v114
	v_add_f32_e32 v2, v2, v115
	v_add_f32_e32 v2, v2, v116
	v_cvt_f32_f16_e32 v82, v4
	v_cvt_f32_f16_sdwa v83, v4 dst_sel:DWORD dst_unused:UNUSED_PAD src0_sel:WORD_1
	v_pk_mul_f32 v[118:119], v[88:89], v[88:89]
	v_add_f32_e32 v2, v2, v117
	v_add_f32_e32 v2, v2, v118
	v_cvt_f32_f16_e32 v4, v5
	v_cvt_f32_f16_sdwa v5, v5 dst_sel:DWORD dst_unused:UNUSED_PAD src0_sel:WORD_1
	v_add_f32_e32 v2, v2, v119
	v_fma_mix_f32 v2, v3, v3, v2 op_sel_hi:[1,1,0]
	v_cvt_f32_f16_e32 v84, v6
	v_cvt_f32_f16_sdwa v85, v6 dst_sel:DWORD dst_unused:UNUSED_PAD src0_sel:WORD_1
	v_pk_mul_f32 v[108:109], v[82:83], v[82:83]
	v_fma_mix_f32 v2, v3, v3, v2 op_sel:[1,1,0] op_sel_hi:[1,1,0]
	v_pk_mul_f32 v[110:111], v[4:5], v[4:5]
	v_add_f32_e32 v2, v2, v108
	v_add_f32_e32 v2, v2, v109
	v_add_f32_e32 v2, v2, v110
	v_cvt_f32_f16_e32 v78, v8
	v_cvt_f32_f16_sdwa v79, v8 dst_sel:DWORD dst_unused:UNUSED_PAD src0_sel:WORD_1
	v_pk_mul_f32 v[112:113], v[84:85], v[84:85]
	v_add_f32_e32 v2, v2, v111
	v_add_f32_e32 v2, v2, v112
	v_cvt_f32_f16_e32 v8, v9
	v_cvt_f32_f16_sdwa v9, v9 dst_sel:DWORD dst_unused:UNUSED_PAD src0_sel:WORD_1
	v_add_f32_e32 v2, v2, v113
	v_fma_mix_f32 v2, v7, v7, v2 op_sel_hi:[1,1,0]
	v_cvt_f32_f16_e32 v80, v10
	v_cvt_f32_f16_sdwa v81, v10 dst_sel:DWORD dst_unused:UNUSED_PAD src0_sel:WORD_1
	v_pk_mul_f32 v[102:103], v[78:79], v[78:79]
	v_fma_mix_f32 v2, v7, v7, v2 op_sel:[1,1,0] op_sel_hi:[1,1,0]
	v_pk_mul_f32 v[104:105], v[8:9], v[8:9]
	v_add_f32_e32 v2, v2, v102
	v_add_f32_e32 v2, v2, v103
	v_add_f32_e32 v2, v2, v104
	v_cvt_f32_f16_e32 v54, v24
	v_cvt_f32_f16_sdwa v55, v24 dst_sel:DWORD dst_unused:UNUSED_PAD src0_sel:WORD_1
	v_pk_mul_f32 v[106:107], v[80:81], v[80:81]
	v_add_f32_e32 v2, v2, v105
	v_add_f32_e32 v2, v2, v106
	v_add_f32_e32 v2, v2, v107
	v_fma_mix_f32 v2, v11, v11, v2 op_sel_hi:[1,1,0]
	v_pk_mul_f32 v[100:101], v[54:55], v[54:55]
	v_fma_mix_f32 v2, v11, v11, v2 op_sel:[1,1,0] op_sel_hi:[1,1,0]
	v_cvt_f32_f16_e32 v52, v15
	v_add_f32_e32 v2, v2, v100
	v_add_f32_e32 v2, v2, v101
	v_fma_mix_f32 v2, v25, v25, v2 op_sel_hi:[1,1,0]
	v_cvt_f32_f16_sdwa v53, v15 dst_sel:DWORD dst_unused:UNUSED_PAD src0_sel:WORD_1
	v_fma_mix_f32 v2, v25, v25, v2 op_sel:[1,1,0] op_sel_hi:[1,1,0]
	v_cvt_f32_f16_sdwa v95, v7 dst_sel:DWORD dst_unused:UNUSED_PAD src0_sel:WORD_1
	v_fma_mix_f32 v2, v26, v26, v2 op_sel_hi:[1,1,0]
	v_pk_mul_f32 v[98:99], v[52:53], v[52:53]
	v_fma_mix_f32 v2, v26, v26, v2 op_sel:[1,1,0] op_sel_hi:[1,1,0]
	v_cvt_f32_f16_e32 v94, v7
	v_fma_mix_f32 v2, v27, v27, v2 op_sel_hi:[1,1,0]
	v_cvt_f32_f16_sdwa v97, v11 dst_sel:DWORD dst_unused:UNUSED_PAD src0_sel:WORD_1
	v_fma_mix_f32 v2, v27, v27, v2 op_sel:[1,1,0] op_sel_hi:[1,1,0]
	v_cvt_f32_f16_e32 v96, v11
	v_fma_mix_f32 v2, v20, v20, v2 op_sel_hi:[1,1,0]
	v_cvt_f32_f16_e32 v195, v12
	v_fma_mix_f32 v2, v20, v20, v2 op_sel:[1,1,0] op_sel_hi:[1,1,0]
	v_cvt_f32_f16_sdwa v196, v12 dst_sel:DWORD dst_unused:UNUSED_PAD src0_sel:WORD_1
	v_fma_mix_f32 v2, v21, v21, v2 op_sel_hi:[1,1,0]
	v_cvt_f32_f16_sdwa v15, v3 dst_sel:DWORD dst_unused:UNUSED_PAD src0_sel:WORD_1
	v_fma_mix_f32 v2, v21, v21, v2 op_sel:[1,1,0] op_sel_hi:[1,1,0]
	v_cvt_f32_f16_e32 v161, v22
	v_fma_mix_f32 v2, v22, v22, v2 op_sel_hi:[1,1,0]
	v_cvt_f32_f16_sdwa v162, v22 dst_sel:DWORD dst_unused:UNUSED_PAD src0_sel:WORD_1
	v_fma_mix_f32 v2, v22, v22, v2 op_sel:[1,1,0] op_sel_hi:[1,1,0]
	v_cvt_f32_f16_e32 v199, v14
	v_fma_mix_f32 v2, v23, v23, v2 op_sel_hi:[1,1,0]
	v_cvt_f32_f16_sdwa v22, v14 dst_sel:DWORD dst_unused:UNUSED_PAD src0_sel:WORD_1
	v_fma_mix_f32 v2, v23, v23, v2 op_sel:[1,1,0] op_sel_hi:[1,1,0]
	v_cvt_f32_f16_e32 v126, v26
	v_fma_mix_f32 v2, v16, v16, v2 op_sel_hi:[1,1,0]
	v_cvt_f32_f16_sdwa v127, v26 dst_sel:DWORD dst_unused:UNUSED_PAD src0_sel:WORD_1
	v_fma_mix_f32 v2, v16, v16, v2 op_sel:[1,1,0] op_sel_hi:[1,1,0]
	v_cvt_f32_f16_e32 v128, v27
	v_fma_mix_f32 v2, v17, v17, v2 op_sel_hi:[1,1,0]
	v_cvt_f32_f16_e32 v24, v25
	v_fma_mix_f32 v2, v17, v17, v2 op_sel:[1,1,0] op_sel_hi:[1,1,0]
	v_cvt_f32_f16_sdwa v30, v25 dst_sel:DWORD dst_unused:UNUSED_PAD src0_sel:WORD_1
	v_fma_mix_f32 v2, v18, v18, v2 op_sel_hi:[1,1,0]
	v_cvt_f32_f16_sdwa v156, v27 dst_sel:DWORD dst_unused:UNUSED_PAD src0_sel:WORD_1
	v_fma_mix_f32 v2, v18, v18, v2 op_sel:[1,1,0] op_sel_hi:[1,1,0]
	v_cvt_f32_f16_e32 v157, v20
	v_fma_mix_f32 v2, v19, v19, v2 op_sel_hi:[1,1,0]
	v_cvt_f32_f16_sdwa v158, v20 dst_sel:DWORD dst_unused:UNUSED_PAD src0_sel:WORD_1
	v_fma_mix_f32 v2, v19, v19, v2 op_sel:[1,1,0] op_sel_hi:[1,1,0]
	v_cvt_f32_f16_e32 v159, v21
	v_fma_mix_f32 v2, v12, v12, v2 op_sel_hi:[1,1,0]
	v_cvt_f32_f16_e32 v163, v23
	v_fma_mix_f32 v2, v12, v12, v2 op_sel:[1,1,0] op_sel_hi:[1,1,0]
	v_cvt_f32_f16_sdwa v160, v21 dst_sel:DWORD dst_unused:UNUSED_PAD src0_sel:WORD_1
	v_fma_mix_f32 v2, v13, v13, v2 op_sel_hi:[1,1,0]
	v_cvt_f32_f16_sdwa v164, v23 dst_sel:DWORD dst_unused:UNUSED_PAD src0_sel:WORD_1
	v_fma_mix_f32 v2, v13, v13, v2 op_sel:[1,1,0] op_sel_hi:[1,1,0]
	v_cvt_f32_f16_e32 v165, v16
	v_fma_mix_f32 v2, v14, v14, v2 op_sel_hi:[1,1,0]
	v_cvt_f32_f16_e32 v191, v18
	v_fma_mix_f32 v2, v14, v14, v2 op_sel:[1,1,0] op_sel_hi:[1,1,0]
	v_cvt_f32_f16_e32 v14, v3
	v_add_f32_e32 v2, v2, v98
	v_add_f32_e32 v2, v2, v99
	v_mov_b32_e32 v6, v2
	s_nop 1
	v_permlane32_swap_b32_e32 v2, v6
	v_add_f32_e32 v2, v2, v6
	v_fmamk_f32 v2, v2, 0x3c000000, v185
	v_mul_f32_e32 v6, 0x4f800000, v2
	v_cmp_gt_f32_e32 vcc, s61, v2
	v_cvt_f32_f16_sdwa v188, v16 dst_sel:DWORD dst_unused:UNUSED_PAD src0_sel:WORD_1
	v_cvt_f32_f16_sdwa v192, v18 dst_sel:DWORD dst_unused:UNUSED_PAD src0_sel:WORD_1
	v_cndmask_b32_e32 v2, v2, v6, vcc
	v_sqrt_f32_e32 v6, v2
	v_cvt_f32_f16_e32 v189, v17
	v_cvt_f32_f16_e32 v193, v19
	v_cvt_f32_f16_sdwa v190, v17 dst_sel:DWORD dst_unused:UNUSED_PAD src0_sel:WORD_1
	v_add_u32_e32 v7, -1, v6
	v_add_u32_e32 v10, 1, v6
	v_fma_f32 v11, -v7, v6, v2
	v_fma_f32 v12, -v10, v6, v2
	v_cmp_ge_f32_e64 s[0:1], 0, v11
	v_cvt_f32_f16_sdwa v194, v19 dst_sel:DWORD dst_unused:UNUSED_PAD src0_sel:WORD_1
	v_cvt_f32_f16_e32 v197, v13
	v_cndmask_b32_e64 v6, v6, v7, s[0:1]
	v_cmp_lt_f32_e64 s[0:1], 0, v12
	v_cvt_f32_f16_sdwa v198, v13 dst_sel:DWORD dst_unused:UNUSED_PAD src0_sel:WORD_1
	v_cvt_f32_f16_sdwa v77, v31 dst_sel:DWORD dst_unused:UNUSED_PAD src0_sel:WORD_1
	v_cndmask_b32_e64 v6, v6, v10, s[0:1]
	v_mul_f32_e32 v7, 0x37800000, v6
	v_cndmask_b32_e32 v6, v6, v7, vcc
	v_cmp_class_f32_e32 vcc, v2, v186
	v_cvt_f32_f16_e32 v76, v31
	s_nop 0
	v_cndmask_b32_e32 v2, v6, v2, vcc
	v_div_scale_f32 v6, s[0:1], v2, v2, 1.0
	v_rcp_f32_e32 v7, v6
	v_div_scale_f32 v3, vcc, 1.0, v2, 1.0
	v_fma_f32 v10, -v6, v7, 1.0
	v_fmac_f32_e32 v7, v10, v7
	v_mul_f32_e32 v10, v3, v7
	v_fma_f32 v11, -v6, v10, v3
	v_fmac_f32_e32 v10, v11, v7
	v_fma_f32 v3, -v6, v10, v3
	v_div_fmas_f32 v3, v3, v7, v10
	v_div_fixup_f32 v10, v3, v2, 1.0
	v_pk_mul_f32 v[0:1], v[10:11], v[0:1] op_sel_hi:[0,1]
	s_waitcnt lgkmcnt(0)
	v_pk_mul_f32 v[0:1], v[58:59], v[0:1]
	v_pk_mul_f32 v[2:3], v[10:11], v[90:91] op_sel_hi:[0,1]
	v_cvt_pk_f16_f32 v99, v0, v1
	v_pk_mul_f32 v[0:1], v[10:11], v[14:15] op_sel_hi:[0,1]
	v_pk_mul_f32 v[0:1], v[62:63], v[0:1]
	v_pk_mul_f32 v[2:3], v[32:33], v[2:3]
	v_cvt_pk_f16_f32 v101, v0, v1
	v_pk_mul_f32 v[0:1], v[10:11], v[82:83] op_sel_hi:[0,1]
	v_pk_mul_f32 v[0:1], v[64:65], v[0:1]
	v_pk_mul_f32 v[6:7], v[10:11], v[92:93] op_sel_hi:[0,1]
	v_cvt_pk_f16_f32 v102, v0, v1
	v_pk_mul_f32 v[0:1], v[10:11], v[84:85] op_sel_hi:[0,1]
	v_pk_mul_f32 v[0:1], v[68:69], v[0:1]
	v_cvt_pk_f16_f32 v106, v2, v3
	v_cvt_pk_f16_f32 v104, v0, v1
	v_pk_mul_f32 v[0:1], v[10:11], v[4:5] op_sel_hi:[0,1]
	v_pk_mul_f32 v[0:1], v[66:67], v[0:1]
	v_mul_f32_e32 v2, v10, v156
	v_cvt_pk_f16_f32 v103, v0, v1
	v_pk_mul_f32 v[0:1], v[10:11], v[94:95] op_sel_hi:[0,1]
	v_pk_mul_f32 v[0:1], v[70:71], v[0:1]
	v_pk_mul_f32 v[6:7], v[36:37], v[6:7]
	v_cvt_pk_f16_f32 v105, v0, v1
	v_pk_mul_f32 v[0:1], v[10:11], v[78:79] op_sel_hi:[0,1]
	v_pk_mul_f32 v[0:1], v[72:73], v[0:1]
	v_cvt_pk_f16_f32 v108, v6, v7
	v_cvt_pk_f16_f32 v110, v0, v1
	v_pk_mul_f32 v[0:1], v[10:11], v[80:81] op_sel_hi:[0,1]
	v_pk_mul_f32 v[0:1], v[48:49], v[0:1]
	v_pk_mul_f32 v[12:13], v[10:11], v[28:29] op_sel_hi:[0,1]
	v_cvt_pk_f16_f32 v112, v0, v1
	v_pk_mul_f32 v[0:1], v[10:11], v[8:9] op_sel_hi:[0,1]
	v_pk_mul_f32 v[0:1], v[74:75], v[0:1]
	v_mul_f32_e32 v9, v43, v2
	v_cvt_pk_f16_f32 v111, v0, v1
	v_pk_mul_f32 v[0:1], v[10:11], v[96:97] op_sel_hi:[0,1]
	v_pk_mul_f32 v[0:1], v[50:51], v[0:1]
	v_pk_mul_f32 v[16:17], v[10:11], v[76:77] op_sel_hi:[0,1]
	v_cvt_pk_f16_f32 v113, v0, v1
	v_mul_f32_e32 v0, v10, v126
	v_mul_f32_e32 v4, v40, v0
	v_pk_mul_f32 v[0:1], v[10:11], v[54:55] op_sel_hi:[0,1]
	v_pk_mul_f32 v[0:1], v[44:45], v[0:1]
	v_pk_mul_f32 v[18:19], v[10:11], v[86:87] op_sel_hi:[0,1]
	v_cvt_pk_f16_f32 v118, v0, v1
	v_mul_f32_e32 v0, v10, v127
	v_mul_f32_e32 v1, v10, v128
	v_mul_f32_e32 v5, v41, v0
	v_mul_f32_e32 v0, v10, v24
	v_mul_f32_e32 v8, v42, v1
	v_mul_f32_e32 v1, v10, v30
	v_mul_f32_e32 v0, v46, v0
	v_mul_f32_e32 v1, v47, v1
	v_cvt_pk_f16_f32 v119, v0, v1
	ds_read_b128 v[0:3], v129 offset:320
	v_cvt_pk_f16_f32 v120, v4, v5
	ds_read_b128 v[4:7], v129 offset:336
	v_cvt_pk_f16_f32 v121, v8, v9
	v_mul_f32_e32 v8, v10, v157
	s_waitcnt lgkmcnt(1)
	v_mul_f32_e32 v0, v0, v8
	v_mul_f32_e32 v8, v10, v161
	s_waitcnt lgkmcnt(0)
	v_mul_f32_e32 v4, v4, v8
	v_mul_f32_e32 v8, v10, v158
	v_mul_f32_e32 v1, v1, v8
	v_mul_f32_e32 v8, v10, v162
	v_mul_f32_e32 v5, v5, v8
	v_mul_f32_e32 v8, v10, v159
	v_mul_f32_e32 v2, v2, v8
	v_mul_f32_e32 v8, v10, v163
	v_mul_f32_e32 v8, v6, v8
	v_mul_f32_e32 v6, v10, v160
	v_mul_f32_e32 v3, v3, v6
	v_mul_f32_e32 v6, v10, v164
	v_cvt_pk_f16_f32 v122, v0, v1
	v_cvt_pk_f16_f32 v123, v2, v3
	ds_read_b128 v[0:3], v129 offset:384
	v_mul_f32_e32 v9, v7, v6
	v_cvt_pk_f16_f32 v124, v4, v5
	ds_read_b128 v[4:7], v129 offset:400
	v_cvt_pk_f16_f32 v125, v8, v9
	v_mul_f32_e32 v8, v10, v165
	s_waitcnt lgkmcnt(1)
	v_mul_f32_e32 v0, v0, v8
	v_mul_f32_e32 v8, v10, v191
	s_waitcnt lgkmcnt(0)
	v_mul_f32_e32 v4, v4, v8
	v_mul_f32_e32 v8, v10, v188
	v_mul_f32_e32 v1, v1, v8
	v_mul_f32_e32 v8, v10, v192
	v_mul_f32_e32 v5, v5, v8
	v_mul_f32_e32 v8, v10, v189
	v_mul_f32_e32 v2, v2, v8
	v_mul_f32_e32 v8, v10, v193
	v_mul_f32_e32 v8, v6, v8
	v_mul_f32_e32 v6, v10, v190
	v_mul_f32_e32 v3, v3, v6
	v_mul_f32_e32 v6, v10, v194
	v_cvt_pk_f16_f32 v126, v0, v1
	v_cvt_pk_f16_f32 v127, v2, v3
	ds_read_b128 v[0:3], v129 offset:448
	v_mul_f32_e32 v9, v7, v6
	v_cvt_pk_f16_f32 v128, v4, v5
	ds_read_b128 v[4:7], v129 offset:464
	v_cvt_pk_f16_f32 v129, v8, v9
	v_mul_f32_e32 v8, v10, v195
	s_waitcnt lgkmcnt(1)
	v_mul_f32_e32 v0, v0, v8
	v_mul_f32_e32 v8, v10, v199
	s_waitcnt lgkmcnt(0)
	v_mul_f32_e32 v4, v4, v8
	v_mul_f32_e32 v8, v10, v196
	v_mul_f32_e32 v1, v1, v8
	v_mul_f32_e32 v8, v10, v22
	v_mul_f32_e32 v5, v5, v8
	v_mul_f32_e32 v8, v10, v197
	v_mul_f32_e32 v2, v2, v8
	v_mul_f32_e32 v8, v10, v52
	v_mul_f32_e32 v6, v6, v8
	v_mul_f32_e32 v8, v10, v198
	v_pk_mul_f32 v[20:21], v[10:11], v[88:89] op_sel_hi:[0,1]
	v_mul_f32_e32 v3, v3, v8
	v_mul_f32_e32 v8, v10, v53
	v_pk_mul_f32 v[12:13], v[34:35], v[12:13]
	v_pk_mul_f32 v[16:17], v[38:39], v[16:17]
	v_pk_mul_f32 v[18:19], v[56:57], v[18:19]
	v_pk_mul_f32 v[20:21], v[60:61], v[20:21]
	v_mul_f32_e32 v7, v7, v8
	v_cvt_pk_f16_f32 v107, v12, v13
	v_cvt_pk_f16_f32 v109, v16, v17
	v_cvt_pk_f16_f32 v98, v18, v19
	v_cvt_pk_f16_f32 v100, v20, v21
	v_cvt_pk_f16_f32 v114, v0, v1
	v_cvt_pk_f16_f32 v115, v2, v3
	v_cvt_pk_f16_f32 v116, v4, v5
	v_cvt_pk_f16_f32 v117, v6, v7
	s_barrier
	s_cbranch_scc1 .LBB0_1630
	v_add_u32_e32 v0, s77, v182
	v_mov_b32_e32 v64, 0
	s_add_i32 s83, s78, -2
	s_mov_b32 s82, 2
	v_lshl_add_u32 v65, v0, 2, s54
	v_lshl_add_u32 v188, s78, 8, v183
	v_mov_b32_e32 v189, v184
	s_mov_b64 s[0:1], s[46:47]
	v_mov_b32_e32 v0, 0
	v_mov_b32_e32 v1, v64
	v_mov_b32_e32 v2, v64
	v_mov_b32_e32 v3, v64
	v_mov_b32_e32 v4, v64
	v_mov_b32_e32 v5, v64
	v_mov_b32_e32 v6, v64
	v_mov_b32_e32 v7, v64
	v_mov_b32_e32 v8, v64
	v_mov_b32_e32 v9, v64
	v_mov_b32_e32 v10, v64
	v_mov_b32_e32 v11, v64
	v_mov_b32_e32 v12, v64
	v_mov_b32_e32 v13, v64
	v_mov_b32_e32 v14, v64
	v_mov_b32_e32 v15, v64
	v_mov_b32_e32 v16, 0
	v_mov_b32_e32 v17, v64
	v_mov_b32_e32 v18, v64
	v_mov_b32_e32 v19, v64
	v_mov_b32_e32 v20, v64
	v_mov_b32_e32 v21, v64
	v_mov_b32_e32 v22, v64
	v_mov_b32_e32 v23, v64
	v_mov_b32_e32 v24, v64
	v_mov_b32_e32 v25, v64
	v_mov_b32_e32 v26, v64
	v_mov_b32_e32 v27, v64
	v_mov_b32_e32 v28, v64
	v_mov_b32_e32 v29, v64
	v_mov_b32_e32 v30, v64
	v_mov_b32_e32 v31, v64
	v_mov_b32_e32 v32, 0
	v_mov_b32_e32 v33, v64
	v_mov_b32_e32 v34, v64
	v_mov_b32_e32 v35, v64
	v_mov_b32_e32 v36, v64
	v_mov_b32_e32 v37, v64
	v_mov_b32_e32 v38, v64
	v_mov_b32_e32 v39, v64
	v_mov_b32_e32 v40, v64
	v_mov_b32_e32 v41, v64
	v_mov_b32_e32 v42, v64
	v_mov_b32_e32 v43, v64
	v_mov_b32_e32 v44, v64
	v_mov_b32_e32 v45, v64
	v_mov_b32_e32 v46, v64
	v_mov_b32_e32 v47, v64
	v_mov_b32_e32 v48, 0
	v_mov_b32_e32 v49, v64
	v_mov_b32_e32 v50, v64
	v_mov_b32_e32 v51, v64
	v_mov_b32_e32 v52, v64
	v_mov_b32_e32 v53, v64
	v_mov_b32_e32 v54, v64
	v_mov_b32_e32 v55, v64
	v_mov_b32_e32 v56, v64
	v_mov_b32_e32 v57, v64
	v_mov_b32_e32 v58, v64
	v_mov_b32_e32 v59, v64
	v_mov_b32_e32 v60, v64
	v_mov_b32_e32 v61, v64
	v_mov_b32_e32 v62, v64
	v_mov_b32_e32 v63, v64
